# GDN step loop software-pipelined + batched split-K slab loads in norm + pipelined X+=acc GEMM epilogue
# speedup vs baseline: 1.0389x; 1.0389x over previous
;     ...
;             if (r < TT) { const float* src = srcP ? (r < TP ? srcP + (size_t)r * DM : srcS + (size_t)(r - TP) * DM) : X + (size_t)r * DM;
; #pragma unroll
;                 for (int i = 0; i < 4; ++i) v[b][i] = *(const f32x4*)(src + i * 256 + lane * 4); } }
; #pragma unroll
;         for (int b = 0; b < 4; ++b) { const int r = r0 + b * nw;
;             if (r < TT) {
;                 float ss = 0.f;
; #pragma unroll
;                 for (int i = 0; i < 4; ++i) {
;                     if (nsl && r >= TP) {
;                         const float* s = scr + (size_t)(r - TP) * DM + i * 256 + lane * 4;
;                         for (int q = 0; q < nsl; ++q) v[b][i] = v[b][i] + *(const f32x4*)(s + (size_t)q * TS * DM);
;                         if (!final_inplace) *(f32x4*)(X + (size_t)r * DM + i * 256 + lane * 4) = v[b][i]; }
.LBB0_28:
	s_or_b64 exec, exec, s[8:9]
	v_add_u32_e32 v16, 0xffffc000, v82
	v_lshlrev_b64 v[108:109], 12, v[16:17]
	v_mov_b32_e32 v83, v17
	v_lshl_add_u64 v[110:111], v[84:85], 0, v[108:109]
	v_lshlrev_b64 v[108:109], 12, v[82:83]
	v_cmp_lt_i32_e64 s[48:49], s15, v82
	v_lshl_add_u64 v[108:109], v[86:87], 0, v[108:109]
	s_and_saveexec_b64 s[8:9], s[48:49]
	s_cbranch_execz .LBB0_33
	global_load_dwordx4 v[120:123], v[110:111], off
	global_load_dwordx4 v[124:127], v[110:111], off offset:1024
	global_load_dwordx4 v[128:131], v[110:111], off offset:2048
	global_load_dwordx4 v[132:135], v[110:111], off offset:3072
	v_add_co_u32_e32 v136, vcc, 0x200000, v110
	s_nop 1
	v_addc_co_u32_e32 v137, vcc, 0, v111, vcc
	global_load_dwordx4 v[140:143], v[136:137], off
	global_load_dwordx4 v[144:147], v[136:137], off offset:1024
	global_load_dwordx4 v[148:151], v[136:137], off offset:2048
	global_load_dwordx4 v[152:155], v[136:137], off offset:3072
	v_add_co_u32_e32 v188, vcc, 0x400000, v110
	s_nop 1
	v_addc_co_u32_e32 v189, vcc, 0, v111, vcc
	global_load_dwordx4 v[156:159], v[188:189], off
	global_load_dwordx4 v[160:163], v[188:189], off offset:1024
	global_load_dwordx4 v[164:167], v[188:189], off offset:2048
	global_load_dwordx4 v[168:171], v[188:189], off offset:3072
	v_add_co_u32_e32 v190, vcc, 0x600000, v110
	s_nop 1
	v_addc_co_u32_e32 v191, vcc, 0, v111, vcc
	global_load_dwordx4 v[172:175], v[190:191], off
	global_load_dwordx4 v[176:179], v[190:191], off offset:1024
	global_load_dwordx4 v[180:183], v[190:191], off offset:2048
	global_load_dwordx4 v[184:187], v[190:191], off offset:3072
	s_waitcnt vmcnt(0)
	v_pk_add_f32 v[78:79], v[78:79], v[120:121]
	v_pk_add_f32 v[80:81], v[80:81], v[122:123]
	v_pk_add_f32 v[78:79], v[78:79], v[140:141]
	v_pk_add_f32 v[80:81], v[80:81], v[142:143]
	v_pk_add_f32 v[78:79], v[78:79], v[156:157]
	v_pk_add_f32 v[80:81], v[80:81], v[158:159]
	v_pk_add_f32 v[78:79], v[78:79], v[172:173]
	v_pk_add_f32 v[80:81], v[80:81], v[174:175]
	v_pk_add_f32 v[74:75], v[74:75], v[124:125]
	v_pk_add_f32 v[76:77], v[76:77], v[126:127]
	v_pk_add_f32 v[74:75], v[74:75], v[144:145]
	v_pk_add_f32 v[76:77], v[76:77], v[146:147]
	v_pk_add_f32 v[74:75], v[74:75], v[160:161]
	v_pk_add_f32 v[76:77], v[76:77], v[162:163]
	v_pk_add_f32 v[74:75], v[74:75], v[176:177]
	v_pk_add_f32 v[76:77], v[76:77], v[178:179]
	v_pk_add_f32 v[70:71], v[70:71], v[128:129]
	v_pk_add_f32 v[72:73], v[72:73], v[130:131]
	v_pk_add_f32 v[70:71], v[70:71], v[148:149]
	v_pk_add_f32 v[72:73], v[72:73], v[150:151]
	v_pk_add_f32 v[70:71], v[70:71], v[164:165]
	v_pk_add_f32 v[72:73], v[72:73], v[166:167]
	v_pk_add_f32 v[70:71], v[70:71], v[180:181]
	v_pk_add_f32 v[72:73], v[72:73], v[182:183]
	v_pk_add_f32 v[66:67], v[66:67], v[132:133]
	v_pk_add_f32 v[68:69], v[68:69], v[134:135]
	v_pk_add_f32 v[66:67], v[66:67], v[152:153]
	v_pk_add_f32 v[68:69], v[68:69], v[154:155]
	v_pk_add_f32 v[66:67], v[66:67], v[168:169]
	v_pk_add_f32 v[68:69], v[68:69], v[170:171]
	v_pk_add_f32 v[66:67], v[66:67], v[184:185]
	v_pk_add_f32 v[68:69], v[68:69], v[186:187]
	global_store_dwordx4 v[108:109], v[78:81], off
	global_store_dwordx4 v[108:109], v[74:77], off offset:1024
	global_store_dwordx4 v[108:109], v[70:73], off offset:2048
	global_store_dwordx4 v[108:109], v[66:69], off offset:3072

;     ...
;         for (int b = 0; b < 4; ++b) { const int r = r0 + b * nw;
;             if (r < TT) {
;                 float ss = 0.f;
; #pragma unroll
;                 for (int i = 0; i < 4; ++i) {
;                     if (nsl && r >= TP) {
;                         const float* s = scr + (size_t)(r - TP) * DM + i * 256 + lane * 4;
;                         for (int q = 0; q < nsl; ++q) v[b][i] = v[b][i] + *(const f32x4*)(s + (size_t)q * TS * DM);
;                         if (!final_inplace) *(f32x4*)(X + (size_t)r * DM + i * 256 + lane * 4) = v[b][i]; }
.LBB0_35:
	s_or_b64 exec, exec, s[8:9]
	s_and_saveexec_b64 s[8:9], s[42:43]
	s_cbranch_execz .LBB0_21
	s_branch .LBB0_51
.LBB0_39:
	v_add_u32_e32 v16, 0xffffc000, v106
	v_lshlrev_b64 v[66:67], 12, v[16:17]
	v_mov_b32_e32 v107, v17
	v_lshl_add_u64 v[68:69], v[84:85], 0, v[66:67]
	v_lshlrev_b64 v[66:67], 12, v[106:107]
	v_cmp_lt_i32_e64 s[46:47], s15, v106
	v_lshl_add_u64 v[66:67], v[86:87], 0, v[66:67]
	s_and_saveexec_b64 s[10:11], s[46:47]
	s_cbranch_execnz .LBB0_55
	s_or_b64 exec, exec, s[10:11]
	s_and_saveexec_b64 s[10:11], s[46:47]
	s_cbranch_execnz .LBB0_56

; #define LAS __attribute__((address_space(3)))
; __device__ __forceinline__ float red16(float x) { x = red8(x); x += dppf<0x140>(x); return x; }
; __device__ __forceinline__ void gdn_group8(float (&S)[4], float (&pp)[16], int j0, const LAS float* L, int sbase_, int kg, int vl) {
;     typedef RecCfg<1> C;
;     f32x4 q[8], k[8]; f32x2 sc[8]; float v[8];
; #pragma unroll
;     for (int j = 0; j < 8; ++j) { const int s = sbase_ + j;
;         q[j] = *(const LAS f32x4*)(L + C::OFF_Q + s * 64 + kg * 4); k[j] = *(const LAS f32x4*)(L + C::OFF_K + s * 64 + kg * 4);
;         sc[j] = *(const LAS f32x2*)(L + C::OFF_SC + s * 4); v[j] = L[C::OFF_V + s * 32 + vl]; }
;     __builtin_amdgcn_sched_barrier(0);
;     f32x2 s0 = (f32x2){S[0], S[1]}, s1 = (f32x2){S[2], S[3]};
; #pragma unroll
;     for (int j = 0; j < 8; ++j) {
;         const f32x2 k0 = (f32x2){k[j][0], k[j][1]}, k1 = (f32x2){k[j][2], k[j][3]};
;         f32x2 r2 = s0 * k0; r2 = s1 * k1 + r2;
;         const float r = red16(r2.x + r2.y);
;         const float u = sc[j][1] * (v[j] - sc[j][0] * r);
;         const f32x2 uu = (f32x2){u, u}, aa = (f32x2){sc[j][0], sc[j][0]};
;         s0 = s0 * aa + k0 * uu; s1 = s1 * aa + k1 * uu;
;         f32x2 p2 = s0 * (f32x2){q[j][0], q[j][1]}; p2 = s1 * (f32x2){q[j][2], q[j][3]} + p2;
;         pp[j0 + j] = p2.x + p2.y;
;     }
;     S[0] = s0.x; S[1] = s0.y; S[2] = s1.x; S[3] = s1.y;
; }
;     ...
;             for (int g = 0; g < (act ? 4 : 0); ++g) { float pp[16];
;                 gdn_group8(S, pp, 0, Lc, g * 16, kg, vl); gdn_group8(S, pp, 8, Lc, g * 16 + 8, kg, vl);
;                 Lc[C::OFF_O + (g * 16 + kg) * 32 + vl] = reduce_scatter16(pp, kg); }
.LBB0_411:
	s_lshl_b32 s5, s22, 2
	s_mov_b32 s8, 4
	s_add_i32 s2, s17, s5
	v_add_u32_e32 v172, s5, v26
	v_add_u32_e32 v173, s5, v25
	v_mov_b32_e32 v174, s2
	v_bfrev_b32_e32 v175, v20
	s_movk_i32 s3, 0x4400
	v_lshrrev_b32_e32 v175, 28, v175
	v_lshlrev_b32_e32 v175, 7, v175
	v_add3_u32 v175, v175, v173, s3
	ds_read_b128 v[28:31], v172 offset:0
	ds_read_b128 v[32:35], v172 offset:16384
	ds_read_b128 v[36:39], v172 offset:256
	ds_read_b128 v[40:43], v172 offset:16640
	ds_read_b128 v[44:47], v172 offset:512
	ds_read_b128 v[48:51], v172 offset:16896
	ds_read_b128 v[52:55], v172 offset:768
	ds_read_b128 v[56:59], v172 offset:17152
	ds_read2_b32 v[60:61], v173 offset1:32
	ds_read2_b32 v[62:63], v173 offset0:64 offset1:96
	ds_read2_b64 v[64:67], v174 offset1:2
	ds_read2_b64 v[68:71], v174 offset0:4 offset1:6
	v_add_u32_e32 v172, 0x400, v172
	v_add_u32_e32 v173, 0x200, v173
	v_add_u32_e32 v174, 64, v174
.Lgdn_step_loop:
	s_waitcnt lgkmcnt(0)
	v_pk_mul_f32 v[158:159], v[10:11], v[32:33]
	v_pk_mul_f32 v[160:161], v[10:11], v[64:65] op_sel_hi:[1,0]
	v_pk_fma_f32 v[158:159], v[12:13], v[34:35], v[158:159]
	v_pk_mul_f32 v[162:163], v[12:13], v[64:65] op_sel_hi:[1,0]
	v_add_f32_e32 v168, v158, v159
	ds_read_b128 v[72:75], v172 offset:0
	ds_read_b128 v[76:79], v172 offset:16384
	v_add_f32_dpp v168, v168, v168 quad_perm:[1,0,3,2] row_mask:0xf bank_mask:0xf bound_ctrl:1
	ds_read_b128 v[80:83], v172 offset:256
	ds_read_b128 v[84:87], v172 offset:16640
	v_add_f32_dpp v168, v168, v168 quad_perm:[2,3,0,1] row_mask:0xf bank_mask:0xf bound_ctrl:1
	ds_read_b128 v[88:91], v172 offset:512
	ds_read_b128 v[92:95], v172 offset:16896
	v_add_f32_dpp v168, v168, v168 row_half_mirror row_mask:0xf bank_mask:0xf bound_ctrl:1
	ds_read_b128 v[96:99], v172 offset:768
	ds_read_b128 v[100:103], v172 offset:17152
	v_add_f32_dpp v168, v168, v168 row_mirror row_mask:0xf bank_mask:0xf bound_ctrl:1
	v_fma_f32 v170, -v64, v168, v60
	v_mul_f32_e32 v170, v65, v170
	v_pk_fma_f32 v[10:11], v[32:33], v[170:171], v[160:161] op_sel_hi:[1,0,1]
	v_pk_fma_f32 v[12:13], v[34:35], v[170:171], v[162:163] op_sel_hi:[1,0,1]
	v_pk_mul_f32 v[158:159], v[10:11], v[40:41]
	v_pk_mul_f32 v[160:161], v[10:11], v[66:67] op_sel_hi:[1,0]
	v_pk_fma_f32 v[158:159], v[12:13], v[42:43], v[158:159]
	v_pk_mul_f32 v[162:163], v[12:13], v[66:67] op_sel_hi:[1,0]
	v_add_f32_e32 v168, v158, v159
	v_pk_mul_f32 v[164:165], v[28:29], v[10:11]
	ds_read2_b32 v[104:105], v173 offset1:32
	v_add_f32_dpp v168, v168, v168 quad_perm:[1,0,3,2] row_mask:0xf bank_mask:0xf bound_ctrl:1
	v_pk_fma_f32 v[164:165], v[30:31], v[12:13], v[164:165]
	ds_read2_b32 v[106:107], v173 offset0:64 offset1:96
	v_add_f32_dpp v168, v168, v168 quad_perm:[2,3,0,1] row_mask:0xf bank_mask:0xf bound_ctrl:1
	v_add_f32_e32 v116, v164, v165
	ds_read2_b64 v[108:111], v174 offset1:2
	v_add_f32_dpp v168, v168, v168 row_half_mirror row_mask:0xf bank_mask:0xf bound_ctrl:1
	ds_read2_b64 v[112:115], v174 offset0:4 offset1:6
	v_add_u32_e32 v172, 0x400, v172
	v_add_f32_dpp v168, v168, v168 row_mirror row_mask:0xf bank_mask:0xf bound_ctrl:1
	v_fma_f32 v170, -v66, v168, v61
	v_mul_f32_e32 v170, v67, v170
	v_pk_fma_f32 v[10:11], v[40:41], v[170:171], v[160:161] op_sel_hi:[1,0,1]
	v_pk_fma_f32 v[12:13], v[42:43], v[170:171], v[162:163] op_sel_hi:[1,0,1]
	v_pk_mul_f32 v[158:159], v[10:11], v[48:49]
	v_pk_mul_f32 v[160:161], v[10:11], v[68:69] op_sel_hi:[1,0]
	v_pk_fma_f32 v[158:159], v[12:13], v[50:51], v[158:159]
	v_pk_mul_f32 v[162:163], v[12:13], v[68:69] op_sel_hi:[1,0]
	v_add_f32_e32 v168, v158, v159
	v_pk_mul_f32 v[166:167], v[36:37], v[10:11]
	v_add_u32_e32 v173, 0x200, v173
	v_add_f32_dpp v168, v168, v168 quad_perm:[1,0,3,2] row_mask:0xf bank_mask:0xf bound_ctrl:1
	v_pk_fma_f32 v[166:167], v[38:39], v[12:13], v[166:167]
	v_add_u32_e32 v174, 64, v174
	v_add_f32_dpp v168, v168, v168 quad_perm:[2,3,0,1] row_mask:0xf bank_mask:0xf bound_ctrl:1
	v_add_f32_e32 v117, v166, v167
	v_add_f32_dpp v140, v116, v116 row_mirror row_mask:0xf bank_mask:0x3 bound_ctrl:1
	v_add_f32_dpp v168, v168, v168 row_half_mirror row_mask:0xf bank_mask:0xf bound_ctrl:1
	v_add_f32_dpp v140, v117, v117 row_mirror row_mask:0xf bank_mask:0xc bound_ctrl:1
	s_add_i32 s8, s8, -1
	v_add_f32_dpp v168, v168, v168 row_mirror row_mask:0xf bank_mask:0xf bound_ctrl:1
	v_fma_f32 v170, -v68, v168, v62
	v_mul_f32_e32 v170, v69, v170
	v_pk_fma_f32 v[10:11], v[48:49], v[170:171], v[160:161] op_sel_hi:[1,0,1]
	v_pk_fma_f32 v[12:13], v[50:51], v[170:171], v[162:163] op_sel_hi:[1,0,1]
	v_pk_mul_f32 v[158:159], v[10:11], v[56:57]
	v_pk_mul_f32 v[160:161], v[10:11], v[70:71] op_sel_hi:[1,0]
	v_pk_fma_f32 v[158:159], v[12:13], v[58:59], v[158:159]
	v_pk_mul_f32 v[162:163], v[12:13], v[70:71] op_sel_hi:[1,0]
	v_add_f32_e32 v168, v158, v159
	v_pk_mul_f32 v[164:165], v[44:45], v[10:11]
	v_add_f32_dpp v148, v140, v140 row_half_mirror row_mask:0xf bank_mask:0x5 bound_ctrl:1
	v_add_f32_dpp v168, v168, v168 quad_perm:[1,0,3,2] row_mask:0xf bank_mask:0xf bound_ctrl:1
	v_pk_fma_f32 v[164:165], v[46:47], v[12:13], v[164:165]
	s_nop 0
	v_add_f32_dpp v168, v168, v168 quad_perm:[2,3,0,1] row_mask:0xf bank_mask:0xf bound_ctrl:1
	v_add_f32_e32 v118, v164, v165
	s_nop 0
	v_add_f32_dpp v168, v168, v168 row_half_mirror row_mask:0xf bank_mask:0xf bound_ctrl:1
	v_add_f32_dpp v141, v118, v118 row_mirror row_mask:0xf bank_mask:0x3 bound_ctrl:1
	s_nop 0
	v_add_f32_dpp v168, v168, v168 row_mirror row_mask:0xf bank_mask:0xf bound_ctrl:1
	v_fma_f32 v170, -v70, v168, v63
	v_mul_f32_e32 v170, v71, v170
	v_pk_fma_f32 v[10:11], v[56:57], v[170:171], v[160:161] op_sel_hi:[1,0,1]
	v_pk_fma_f32 v[12:13], v[58:59], v[170:171], v[162:163] op_sel_hi:[1,0,1]
	s_waitcnt lgkmcnt(0)
; template <int CTRL> __device__ __forceinline__ float dppf(float x) { return __builtin_bit_cast(float, __builtin_amdgcn_update_dpp(0, __builtin_bit_cast(int, x), CTRL, 0xF, 0xF, true)); }
; __device__ __forceinline__ float red16(float x) { x = red8(x); x += dppf<0x140>(x); return x; }
; __device__ __forceinline__ void gdn_group8(float (&S)[4], float (&pp)[16], int j0, const LAS float* L, int sbase_, int kg, int vl) {
;     ...
;     for (int j = 0; j < 8; ++j) {
;         const f32x2 k0 = (f32x2){k[j][0], k[j][1]}, k1 = (f32x2){k[j][2], k[j][3]};
;         f32x2 r2 = s0 * k0; r2 = s1 * k1 + r2;
;         const float r = red16(r2.x + r2.y);
;         const float u = sc[j][1] * (v[j] - sc[j][0] * r);
;         const f32x2 uu = (f32x2){u, u}, aa = (f32x2){sc[j][0], sc[j][0]};
;         s0 = s0 * aa + k0 * uu; s1 = s1 * aa + k1 * uu;
;         f32x2 p2 = s0 * (f32x2){q[j][0], q[j][1]}; p2 = s1 * (f32x2){q[j][2], q[j][3]} + p2;
;         pp[j0 + j] = p2.x + p2.y;
;     }
; __device__ __forceinline__ float reduce_scatter16(const float (&p)[16], int kg) {
;     ...
;     for (int j = 0; j < 8; ++j) { const float keep = b3 ? p[j + 8] : p[j], send = b3 ? p[j] : p[j + 8]; t[j] = keep + dppf<0x140>(send); }
; #pragma unroll
;     for (int j = 0; j < 4; ++j) { const float keep = b2 ? t[j + 4] : t[j], send = b2 ? t[j] : t[j + 4]; u[j] = keep + dppf<0x141>(send); }
; #pragma unroll
	v_pk_mul_f32 v[158:159], v[10:11], v[76:77]
	v_pk_mul_f32 v[160:161], v[10:11], v[108:109] op_sel_hi:[1,0]
	v_pk_fma_f32 v[158:159], v[12:13], v[78:79], v[158:159]
	v_pk_mul_f32 v[162:163], v[12:13], v[108:109] op_sel_hi:[1,0]
	v_add_f32_e32 v168, v158, v159
	v_pk_mul_f32 v[166:167], v[52:53], v[10:11]
	s_nop 0
	v_add_f32_dpp v168, v168, v168 quad_perm:[1,0,3,2] row_mask:0xf bank_mask:0xf bound_ctrl:1
	v_pk_fma_f32 v[166:167], v[54:55], v[12:13], v[166:167]
	ds_read_b128 v[28:31], v172 offset:0
	v_add_f32_dpp v168, v168, v168 quad_perm:[2,3,0,1] row_mask:0xf bank_mask:0xf bound_ctrl:1
	v_add_f32_e32 v119, v166, v167
	ds_read_b128 v[32:35], v172 offset:16384
	v_add_f32_dpp v168, v168, v168 row_half_mirror row_mask:0xf bank_mask:0xf bound_ctrl:1
	ds_read_b128 v[36:39], v172 offset:256
	ds_read_b128 v[40:43], v172 offset:16640
	v_add_f32_dpp v168, v168, v168 row_mirror row_mask:0xf bank_mask:0xf bound_ctrl:1
	v_fma_f32 v170, -v108, v168, v104
	v_mul_f32_e32 v170, v109, v170
	v_pk_fma_f32 v[10:11], v[76:77], v[170:171], v[160:161] op_sel_hi:[1,0,1]
	v_pk_fma_f32 v[12:13], v[78:79], v[170:171], v[162:163] op_sel_hi:[1,0,1]
	v_pk_mul_f32 v[158:159], v[10:11], v[84:85]
	v_pk_mul_f32 v[160:161], v[10:11], v[110:111] op_sel_hi:[1,0]
	v_pk_fma_f32 v[158:159], v[12:13], v[86:87], v[158:159]
	v_pk_mul_f32 v[162:163], v[12:13], v[110:111] op_sel_hi:[1,0]
	v_add_f32_e32 v168, v158, v159
	v_pk_mul_f32 v[164:165], v[72:73], v[10:11]
	ds_read_b128 v[44:47], v172 offset:512
	v_add_f32_dpp v168, v168, v168 quad_perm:[1,0,3,2] row_mask:0xf bank_mask:0xf bound_ctrl:1
	v_pk_fma_f32 v[164:165], v[74:75], v[12:13], v[164:165]
	ds_read_b128 v[48:51], v172 offset:16896
	v_add_f32_dpp v168, v168, v168 quad_perm:[2,3,0,1] row_mask:0xf bank_mask:0xf bound_ctrl:1
	v_add_f32_e32 v120, v164, v165
	ds_read_b128 v[52:55], v172 offset:768
	v_add_f32_dpp v168, v168, v168 row_half_mirror row_mask:0xf bank_mask:0xf bound_ctrl:1
	ds_read_b128 v[56:59], v172 offset:17152
	ds_read2_b32 v[60:61], v173 offset1:32
	v_add_f32_dpp v168, v168, v168 row_mirror row_mask:0xf bank_mask:0xf bound_ctrl:1
	v_fma_f32 v170, -v110, v168, v105
	v_mul_f32_e32 v170, v111, v170
	v_pk_fma_f32 v[10:11], v[84:85], v[170:171], v[160:161] op_sel_hi:[1,0,1]
	v_pk_fma_f32 v[12:13], v[86:87], v[170:171], v[162:163] op_sel_hi:[1,0,1]
	v_pk_mul_f32 v[158:159], v[10:11], v[92:93]
	v_pk_mul_f32 v[160:161], v[10:11], v[112:113] op_sel_hi:[1,0]
	v_pk_fma_f32 v[158:159], v[12:13], v[94:95], v[158:159]
	v_pk_mul_f32 v[162:163], v[12:13], v[112:113] op_sel_hi:[1,0]
	v_add_f32_e32 v168, v158, v159
	v_pk_mul_f32 v[166:167], v[80:81], v[10:11]
	ds_read2_b32 v[62:63], v173 offset0:64 offset1:96
	v_add_f32_dpp v168, v168, v168 quad_perm:[1,0,3,2] row_mask:0xf bank_mask:0xf bound_ctrl:1
	v_pk_fma_f32 v[166:167], v[82:83], v[12:13], v[166:167]
	ds_read2_b64 v[64:67], v174 offset1:2
	v_add_f32_dpp v168, v168, v168 quad_perm:[2,3,0,1] row_mask:0xf bank_mask:0xf bound_ctrl:1
	v_add_f32_e32 v121, v166, v167
	ds_read2_b64 v[68:71], v174 offset0:4 offset1:6
	v_add_f32_dpp v168, v168, v168 row_half_mirror row_mask:0xf bank_mask:0xf bound_ctrl:1
	v_add_u32_e32 v172, 0x400, v172
	v_add_u32_e32 v173, 0x200, v173
	v_add_f32_dpp v168, v168, v168 row_mirror row_mask:0xf bank_mask:0xf bound_ctrl:1
	v_fma_f32 v170, -v112, v168, v106
	v_mul_f32_e32 v170, v113, v170
	v_pk_fma_f32 v[10:11], v[92:93], v[170:171], v[160:161] op_sel_hi:[1,0,1]
	v_pk_fma_f32 v[12:13], v[94:95], v[170:171], v[162:163] op_sel_hi:[1,0,1]
	v_pk_mul_f32 v[158:159], v[10:11], v[100:101]
	v_pk_mul_f32 v[160:161], v[10:11], v[114:115] op_sel_hi:[1,0]
	v_pk_fma_f32 v[158:159], v[12:13], v[102:103], v[158:159]
	v_pk_mul_f32 v[162:163], v[12:13], v[114:115] op_sel_hi:[1,0]
	v_add_f32_e32 v168, v158, v159
	v_pk_mul_f32 v[164:165], v[88:89], v[10:11]
	v_add_u32_e32 v174, 64, v174
	v_add_f32_dpp v168, v168, v168 quad_perm:[1,0,3,2] row_mask:0xf bank_mask:0xf bound_ctrl:1
	v_pk_fma_f32 v[164:165], v[90:91], v[12:13], v[164:165]
	v_add_f32_dpp v142, v120, v120 row_mirror row_mask:0xf bank_mask:0x3 bound_ctrl:1
	v_add_f32_dpp v168, v168, v168 quad_perm:[2,3,0,1] row_mask:0xf bank_mask:0xf bound_ctrl:1
	v_add_f32_e32 v122, v164, v165
	v_add_f32_dpp v142, v121, v121 row_mirror row_mask:0xf bank_mask:0xc bound_ctrl:1
	v_add_f32_dpp v168, v168, v168 row_half_mirror row_mask:0xf bank_mask:0xf bound_ctrl:1
	v_add_f32_dpp v143, v122, v122 row_mirror row_mask:0xf bank_mask:0x3 bound_ctrl:1
	v_add_f32_dpp v141, v119, v119 row_mirror row_mask:0xf bank_mask:0xc bound_ctrl:1
	v_add_f32_dpp v168, v168, v168 row_mirror row_mask:0xf bank_mask:0xf bound_ctrl:1
	v_fma_f32 v170, -v114, v168, v107
	v_mul_f32_e32 v170, v115, v170
	v_pk_fma_f32 v[10:11], v[100:101], v[170:171], v[160:161] op_sel_hi:[1,0,1]
	v_pk_fma_f32 v[12:13], v[102:103], v[170:171], v[162:163] op_sel_hi:[1,0,1]
	s_waitcnt lgkmcnt(0)
; template <int CTRL> __device__ __forceinline__ float dppf(float x) { return __builtin_bit_cast(float, __builtin_amdgcn_update_dpp(0, __builtin_bit_cast(int, x), CTRL, 0xF, 0xF, true)); }
; __device__ __forceinline__ float red16(float x) { x = red8(x); x += dppf<0x140>(x); return x; }
; __device__ __forceinline__ void gdn_group8(float (&S)[4], float (&pp)[16], int j0, const LAS float* L, int sbase_, int kg, int vl) {
;     ...
;     for (int j = 0; j < 8; ++j) {
;         const f32x2 k0 = (f32x2){k[j][0], k[j][1]}, k1 = (f32x2){k[j][2], k[j][3]};
;         f32x2 r2 = s0 * k0; r2 = s1 * k1 + r2;
;         const float r = red16(r2.x + r2.y);
;         const float u = sc[j][1] * (v[j] - sc[j][0] * r);
;         const f32x2 uu = (f32x2){u, u}, aa = (f32x2){sc[j][0], sc[j][0]};
;         s0 = s0 * aa + k0 * uu; s1 = s1 * aa + k1 * uu;
;         f32x2 p2 = s0 * (f32x2){q[j][0], q[j][1]}; p2 = s1 * (f32x2){q[j][2], q[j][3]} + p2;
;         pp[j0 + j] = p2.x + p2.y;
;     }
; __device__ __forceinline__ float reduce_scatter16(const float (&p)[16], int kg) {
;     ...
;     for (int j = 0; j < 8; ++j) { const float keep = b3 ? p[j + 8] : p[j], send = b3 ? p[j] : p[j + 8]; t[j] = keep + dppf<0x140>(send); }
; #pragma unroll
;     for (int j = 0; j < 4; ++j) { const float keep = b2 ? t[j + 4] : t[j], send = b2 ? t[j] : t[j + 4]; u[j] = keep + dppf<0x141>(send); }
; #pragma unroll
	v_pk_mul_f32 v[158:159], v[10:11], v[32:33]
	v_pk_mul_f32 v[160:161], v[10:11], v[64:65] op_sel_hi:[1,0]
	v_pk_fma_f32 v[158:159], v[12:13], v[34:35], v[158:159]
	v_pk_mul_f32 v[162:163], v[12:13], v[64:65] op_sel_hi:[1,0]
	v_add_f32_e32 v168, v158, v159
	v_pk_mul_f32 v[166:167], v[96:97], v[10:11]
	v_add_f32_dpp v149, v142, v142 row_half_mirror row_mask:0xf bank_mask:0x5 bound_ctrl:1
	v_add_f32_dpp v168, v168, v168 quad_perm:[1,0,3,2] row_mask:0xf bank_mask:0xf bound_ctrl:1
	v_pk_fma_f32 v[166:167], v[98:99], v[12:13], v[166:167]
	ds_read_b128 v[72:75], v172 offset:0
	v_add_f32_dpp v168, v168, v168 quad_perm:[2,3,0,1] row_mask:0xf bank_mask:0xf bound_ctrl:1
	v_add_f32_e32 v123, v166, v167
	ds_read_b128 v[76:79], v172 offset:16384
	v_add_f32_dpp v168, v168, v168 row_half_mirror row_mask:0xf bank_mask:0xf bound_ctrl:1
	ds_read_b128 v[80:83], v172 offset:256
	ds_read_b128 v[84:87], v172 offset:16640
	v_add_f32_dpp v168, v168, v168 row_mirror row_mask:0xf bank_mask:0xf bound_ctrl:1
	v_fma_f32 v170, -v64, v168, v60
	v_mul_f32_e32 v170, v65, v170
	v_pk_fma_f32 v[10:11], v[32:33], v[170:171], v[160:161] op_sel_hi:[1,0,1]
	v_pk_fma_f32 v[12:13], v[34:35], v[170:171], v[162:163] op_sel_hi:[1,0,1]
	v_pk_mul_f32 v[158:159], v[10:11], v[40:41]
	v_pk_mul_f32 v[160:161], v[10:11], v[66:67] op_sel_hi:[1,0]
	v_pk_fma_f32 v[158:159], v[12:13], v[42:43], v[158:159]
	v_pk_mul_f32 v[162:163], v[12:13], v[66:67] op_sel_hi:[1,0]
	v_add_f32_e32 v168, v158, v159
	v_pk_mul_f32 v[164:165], v[28:29], v[10:11]
	ds_read_b128 v[88:91], v172 offset:512
	v_add_f32_dpp v168, v168, v168 quad_perm:[1,0,3,2] row_mask:0xf bank_mask:0xf bound_ctrl:1
	v_pk_fma_f32 v[164:165], v[30:31], v[12:13], v[164:165]
	ds_read_b128 v[92:95], v172 offset:16896
	v_add_f32_dpp v168, v168, v168 quad_perm:[2,3,0,1] row_mask:0xf bank_mask:0xf bound_ctrl:1
	v_add_f32_e32 v124, v164, v165
	ds_read_b128 v[96:99], v172 offset:768
	v_add_f32_dpp v168, v168, v168 row_half_mirror row_mask:0xf bank_mask:0xf bound_ctrl:1
	ds_read_b128 v[100:103], v172 offset:17152
	ds_read2_b32 v[104:105], v173 offset1:32
	v_add_f32_dpp v168, v168, v168 row_mirror row_mask:0xf bank_mask:0xf bound_ctrl:1
	v_fma_f32 v170, -v66, v168, v61
	v_mul_f32_e32 v170, v67, v170
	v_pk_fma_f32 v[10:11], v[40:41], v[170:171], v[160:161] op_sel_hi:[1,0,1]
	v_pk_fma_f32 v[12:13], v[42:43], v[170:171], v[162:163] op_sel_hi:[1,0,1]
	v_pk_mul_f32 v[158:159], v[10:11], v[48:49]
	v_pk_mul_f32 v[160:161], v[10:11], v[68:69] op_sel_hi:[1,0]
	v_pk_fma_f32 v[158:159], v[12:13], v[50:51], v[158:159]
	v_pk_mul_f32 v[162:163], v[12:13], v[68:69] op_sel_hi:[1,0]
	v_add_f32_e32 v168, v158, v159
	v_pk_mul_f32 v[166:167], v[36:37], v[10:11]
	ds_read2_b32 v[106:107], v173 offset0:64 offset1:96
	v_add_f32_dpp v168, v168, v168 quad_perm:[1,0,3,2] row_mask:0xf bank_mask:0xf bound_ctrl:1
	v_pk_fma_f32 v[166:167], v[38:39], v[12:13], v[166:167]
	ds_read2_b64 v[108:111], v174 offset1:2
	v_add_f32_dpp v168, v168, v168 quad_perm:[2,3,0,1] row_mask:0xf bank_mask:0xf bound_ctrl:1
	v_add_f32_e32 v125, v166, v167
	ds_read2_b64 v[112:115], v174 offset0:4 offset1:6
	v_add_f32_dpp v168, v168, v168 row_half_mirror row_mask:0xf bank_mask:0xf bound_ctrl:1
	v_add_u32_e32 v172, 0x400, v172
	v_add_u32_e32 v173, 0x200, v173
	v_add_f32_dpp v168, v168, v168 row_mirror row_mask:0xf bank_mask:0xf bound_ctrl:1
	v_fma_f32 v170, -v68, v168, v62
	v_mul_f32_e32 v170, v69, v170
	v_pk_fma_f32 v[10:11], v[48:49], v[170:171], v[160:161] op_sel_hi:[1,0,1]
	v_pk_fma_f32 v[12:13], v[50:51], v[170:171], v[162:163] op_sel_hi:[1,0,1]
	v_pk_mul_f32 v[158:159], v[10:11], v[56:57]
	v_pk_mul_f32 v[160:161], v[10:11], v[70:71] op_sel_hi:[1,0]
	v_pk_fma_f32 v[158:159], v[12:13], v[58:59], v[158:159]
	v_pk_mul_f32 v[162:163], v[12:13], v[70:71] op_sel_hi:[1,0]
	v_add_f32_e32 v168, v158, v159
	v_pk_mul_f32 v[164:165], v[44:45], v[10:11]
	v_add_u32_e32 v174, 64, v174
	v_add_f32_dpp v168, v168, v168 quad_perm:[1,0,3,2] row_mask:0xf bank_mask:0xf bound_ctrl:1
	v_pk_fma_f32 v[164:165], v[46:47], v[12:13], v[164:165]
	v_add_f32_dpp v143, v123, v123 row_mirror row_mask:0xf bank_mask:0xc bound_ctrl:1
	v_add_f32_dpp v168, v168, v168 quad_perm:[2,3,0,1] row_mask:0xf bank_mask:0xf bound_ctrl:1
	v_add_f32_e32 v126, v164, v165
	v_add_f32_dpp v144, v124, v124 row_mirror row_mask:0xf bank_mask:0x3 bound_ctrl:1
	v_add_f32_dpp v168, v168, v168 row_half_mirror row_mask:0xf bank_mask:0xf bound_ctrl:1
	v_add_f32_dpp v148, v141, v141 row_half_mirror row_mask:0xf bank_mask:0xa bound_ctrl:1
	v_add_f32_dpp v149, v143, v143 row_half_mirror row_mask:0xf bank_mask:0xa bound_ctrl:1
	v_add_f32_dpp v168, v168, v168 row_mirror row_mask:0xf bank_mask:0xf bound_ctrl:1
	v_fma_f32 v170, -v70, v168, v63
	v_mul_f32_e32 v170, v71, v170
	v_pk_fma_f32 v[10:11], v[56:57], v[170:171], v[160:161] op_sel_hi:[1,0,1]
	v_pk_fma_f32 v[12:13], v[58:59], v[170:171], v[162:163] op_sel_hi:[1,0,1]
	s_waitcnt lgkmcnt(0)
; template <int CTRL> __device__ __forceinline__ float dppf(float x) { return __builtin_bit_cast(float, __builtin_amdgcn_update_dpp(0, __builtin_bit_cast(int, x), CTRL, 0xF, 0xF, true)); }
; __device__ __forceinline__ float red16(float x) { x = red8(x); x += dppf<0x140>(x); return x; }
; __device__ __forceinline__ void gdn_group8(float (&S)[4], float (&pp)[16], int j0, const LAS float* L, int sbase_, int kg, int vl) {
;     ...
;     for (int j = 0; j < 8; ++j) {
;         const f32x2 k0 = (f32x2){k[j][0], k[j][1]}, k1 = (f32x2){k[j][2], k[j][3]};
;         f32x2 r2 = s0 * k0; r2 = s1 * k1 + r2;
;         const float r = red16(r2.x + r2.y);
;         const float u = sc[j][1] * (v[j] - sc[j][0] * r);
;         const f32x2 uu = (f32x2){u, u}, aa = (f32x2){sc[j][0], sc[j][0]};
;         s0 = s0 * aa + k0 * uu; s1 = s1 * aa + k1 * uu;
;         f32x2 p2 = s0 * (f32x2){q[j][0], q[j][1]}; p2 = s1 * (f32x2){q[j][2], q[j][3]} + p2;
;         pp[j0 + j] = p2.x + p2.y;
;     }
; __device__ __forceinline__ float reduce_scatter16(const float (&p)[16], int kg) {
;     const bool b3 = kg & 8, b2 = kg & 4, b1 = kg & 2, b0 = kg & 1;
;     float t[8], u[4], w[2];
; #pragma unroll
;     for (int j = 0; j < 8; ++j) { const float keep = b3 ? p[j + 8] : p[j], send = b3 ? p[j] : p[j + 8]; t[j] = keep + dppf<0x140>(send); }
; #pragma unroll
;     for (int j = 0; j < 4; ++j) { const float keep = b2 ? t[j + 4] : t[j], send = b2 ? t[j] : t[j + 4]; u[j] = keep + dppf<0x141>(send); }
; #pragma unroll
;     for (int j = 0; j < 2; ++j) { const float keep = b1 ? u[j + 2] : u[j], send = b1 ? u[j] : u[j + 2]; w[j] = keep + dppf<0x1B>(send); }
;     const float keep = b0 ? w[1] : w[0], send = b0 ? w[0] : w[1];
;     return keep + dppf<0xB1>(send);
; }
;     ...
;                 Lc[C::OFF_O + (g * 16 + kg) * 32 + vl] = reduce_scatter16(pp, kg); }
	v_pk_mul_f32 v[158:159], v[10:11], v[76:77]
	v_pk_mul_f32 v[160:161], v[10:11], v[108:109] op_sel_hi:[1,0]
	v_pk_fma_f32 v[158:159], v[12:13], v[78:79], v[158:159]
	v_pk_mul_f32 v[162:163], v[12:13], v[108:109] op_sel_hi:[1,0]
	v_add_f32_e32 v168, v158, v159
	v_pk_mul_f32 v[166:167], v[52:53], v[10:11]
	v_add_f32_dpp v144, v125, v125 row_mirror row_mask:0xf bank_mask:0xc bound_ctrl:1
	v_add_f32_dpp v168, v168, v168 quad_perm:[1,0,3,2] row_mask:0xf bank_mask:0xf bound_ctrl:1
	v_pk_fma_f32 v[166:167], v[54:55], v[12:13], v[166:167]
	ds_read_b128 v[28:31], v172 offset:0
	v_add_f32_dpp v168, v168, v168 quad_perm:[2,3,0,1] row_mask:0xf bank_mask:0xf bound_ctrl:1
	v_add_f32_e32 v127, v166, v167
	ds_read_b128 v[32:35], v172 offset:16384
	v_add_f32_dpp v168, v168, v168 row_half_mirror row_mask:0xf bank_mask:0xf bound_ctrl:1
	ds_read_b128 v[36:39], v172 offset:256
	ds_read_b128 v[40:43], v172 offset:16640
	v_add_f32_dpp v168, v168, v168 row_mirror row_mask:0xf bank_mask:0xf bound_ctrl:1
	v_fma_f32 v170, -v108, v168, v104
	v_mul_f32_e32 v170, v109, v170
	v_pk_fma_f32 v[10:11], v[76:77], v[170:171], v[160:161] op_sel_hi:[1,0,1]
	v_pk_fma_f32 v[12:13], v[78:79], v[170:171], v[162:163] op_sel_hi:[1,0,1]
	v_pk_mul_f32 v[158:159], v[10:11], v[84:85]
	v_pk_mul_f32 v[160:161], v[10:11], v[110:111] op_sel_hi:[1,0]
	v_pk_fma_f32 v[158:159], v[12:13], v[86:87], v[158:159]
	v_pk_mul_f32 v[162:163], v[12:13], v[110:111] op_sel_hi:[1,0]
	v_add_f32_e32 v168, v158, v159
	v_pk_mul_f32 v[164:165], v[72:73], v[10:11]
	ds_read_b128 v[44:47], v172 offset:512
	v_add_f32_dpp v168, v168, v168 quad_perm:[1,0,3,2] row_mask:0xf bank_mask:0xf bound_ctrl:1
	v_pk_fma_f32 v[164:165], v[74:75], v[12:13], v[164:165]
	ds_read_b128 v[48:51], v172 offset:16896
	v_add_f32_dpp v168, v168, v168 quad_perm:[2,3,0,1] row_mask:0xf bank_mask:0xf bound_ctrl:1
	v_add_f32_e32 v128, v164, v165
	ds_read_b128 v[52:55], v172 offset:768
	v_add_f32_dpp v168, v168, v168 row_half_mirror row_mask:0xf bank_mask:0xf bound_ctrl:1
	ds_read_b128 v[56:59], v172 offset:17152
	ds_read2_b32 v[60:61], v173 offset1:32
	v_add_f32_dpp v168, v168, v168 row_mirror row_mask:0xf bank_mask:0xf bound_ctrl:1
	v_fma_f32 v170, -v110, v168, v105
	v_mul_f32_e32 v170, v111, v170
	v_pk_fma_f32 v[10:11], v[84:85], v[170:171], v[160:161] op_sel_hi:[1,0,1]
	v_pk_fma_f32 v[12:13], v[86:87], v[170:171], v[162:163] op_sel_hi:[1,0,1]
	v_pk_mul_f32 v[158:159], v[10:11], v[92:93]
	v_pk_mul_f32 v[160:161], v[10:11], v[112:113] op_sel_hi:[1,0]
	v_pk_fma_f32 v[158:159], v[12:13], v[94:95], v[158:159]
	v_pk_mul_f32 v[162:163], v[12:13], v[112:113] op_sel_hi:[1,0]
	v_add_f32_e32 v168, v158, v159
	v_pk_mul_f32 v[166:167], v[80:81], v[10:11]
	ds_read2_b32 v[62:63], v173 offset0:64 offset1:96
	v_add_f32_dpp v168, v168, v168 quad_perm:[1,0,3,2] row_mask:0xf bank_mask:0xf bound_ctrl:1
	v_pk_fma_f32 v[166:167], v[82:83], v[12:13], v[166:167]
	ds_read2_b64 v[64:67], v174 offset1:2
	v_add_f32_dpp v168, v168, v168 quad_perm:[2,3,0,1] row_mask:0xf bank_mask:0xf bound_ctrl:1
	v_add_f32_e32 v129, v166, v167
	ds_read2_b64 v[68:71], v174 offset0:4 offset1:6
	v_add_f32_dpp v168, v168, v168 row_half_mirror row_mask:0xf bank_mask:0xf bound_ctrl:1
	v_add_u32_e32 v172, 0x400, v172
	v_add_u32_e32 v173, 0x200, v173
	v_add_f32_dpp v168, v168, v168 row_mirror row_mask:0xf bank_mask:0xf bound_ctrl:1
	v_fma_f32 v170, -v112, v168, v106
	v_mul_f32_e32 v170, v113, v170
	v_pk_fma_f32 v[10:11], v[92:93], v[170:171], v[160:161] op_sel_hi:[1,0,1]
	v_pk_fma_f32 v[12:13], v[94:95], v[170:171], v[162:163] op_sel_hi:[1,0,1]
	v_pk_mul_f32 v[158:159], v[10:11], v[100:101]
	v_pk_mul_f32 v[160:161], v[10:11], v[114:115] op_sel_hi:[1,0]
	v_pk_fma_f32 v[158:159], v[12:13], v[102:103], v[158:159]
	v_pk_mul_f32 v[162:163], v[12:13], v[114:115] op_sel_hi:[1,0]
	v_add_f32_e32 v168, v158, v159
	v_pk_mul_f32 v[164:165], v[88:89], v[10:11]
	v_add_u32_e32 v174, 64, v174
	v_add_f32_dpp v168, v168, v168 quad_perm:[1,0,3,2] row_mask:0xf bank_mask:0xf bound_ctrl:1
	v_pk_fma_f32 v[164:165], v[90:91], v[12:13], v[164:165]
	v_add_f32_dpp v146, v128, v128 row_mirror row_mask:0xf bank_mask:0x3 bound_ctrl:1
	v_add_f32_dpp v168, v168, v168 quad_perm:[2,3,0,1] row_mask:0xf bank_mask:0xf bound_ctrl:1
	v_add_f32_e32 v130, v164, v165
	v_add_f32_dpp v145, v126, v126 row_mirror row_mask:0xf bank_mask:0x3 bound_ctrl:1
	v_add_f32_dpp v168, v168, v168 row_half_mirror row_mask:0xf bank_mask:0xf bound_ctrl:1
	v_add_f32_dpp v146, v129, v129 row_mirror row_mask:0xf bank_mask:0xc bound_ctrl:1
	v_add_f32_dpp v147, v130, v130 row_mirror row_mask:0xf bank_mask:0x3 bound_ctrl:1
	v_add_f32_dpp v168, v168, v168 row_mirror row_mask:0xf bank_mask:0xf bound_ctrl:1
	v_fma_f32 v170, -v114, v168, v107
	v_mul_f32_e32 v170, v115, v170
	v_pk_fma_f32 v[10:11], v[100:101], v[170:171], v[160:161] op_sel_hi:[1,0,1]
	v_pk_fma_f32 v[12:13], v[102:103], v[170:171], v[162:163] op_sel_hi:[1,0,1]
	v_pk_mul_f32 v[166:167], v[96:97], v[10:11]
	v_cndmask_b32_e64 v154, v149, v148, s[48:49]
	v_pk_fma_f32 v[166:167], v[98:99], v[12:13], v[166:167]
	v_cndmask_b32_e64 v155, v148, v149, s[48:49]
	v_add_f32_e32 v131, v166, v167
	v_add_f32_dpp v145, v127, v127 row_mirror row_mask:0xf bank_mask:0xc bound_ctrl:1
	v_add_f32_dpp v150, v144, v144 row_half_mirror row_mask:0xf bank_mask:0x5 bound_ctrl:1
	v_add_f32_dpp v147, v131, v131 row_mirror row_mask:0xf bank_mask:0xc bound_ctrl:1
	v_add_f32_dpp v151, v146, v146 row_half_mirror row_mask:0xf bank_mask:0x5 bound_ctrl:1
	v_add_f32_dpp v152, v155, v154 quad_perm:[3,2,1,0] row_mask:0xf bank_mask:0xf bound_ctrl:1
	v_add_f32_dpp v150, v145, v145 row_half_mirror row_mask:0xf bank_mask:0xa bound_ctrl:1
	v_add_f32_dpp v151, v147, v147 row_half_mirror row_mask:0xf bank_mask:0xa bound_ctrl:1
	v_cndmask_b32_e64 v154, v151, v150, s[48:49]
	v_cndmask_b32_e64 v155, v150, v151, s[48:49]
	s_nop 1
	v_add_f32_dpp v153, v155, v154 quad_perm:[3,2,1,0] row_mask:0xf bank_mask:0xf bound_ctrl:1
	v_cndmask_b32_e64 v154, v153, v152, s[50:51]
	v_cndmask_b32_e64 v155, v152, v153, s[50:51]
	s_nop 1
	v_add_f32_dpp v156, v155, v154 quad_perm:[1,0,3,2] row_mask:0xf bank_mask:0xf bound_ctrl:1
	ds_write_b32 v175, v156
	v_add_u32_e32 v175, 0x800, v175
	s_cmp_eq_u32 s8, 0
	s_cbranch_scc0 .Lgdn_step_loop
	s_waitcnt lgkmcnt(0)

;     ...
;             if (r < TT) { const float* src = srcP ? (r < TP ? srcP + (size_t)r * DM : srcS + (size_t)(r - TP) * DM) : X + (size_t)r * DM;
; #pragma unroll
;                 for (int i = 0; i < 4; ++i) v[b][i] = *(const f32x4*)(src + i * 256 + lane * 4); } }
; #pragma unroll
;         for (int b = 0; b < 4; ++b) { const int r = r0 + b * nw;
;             if (r < TT) {
;                 float ss = 0.f;
; #pragma unroll
;                 for (int i = 0; i < 4; ++i) {
;                     if (nsl && r >= TP) {
;                         const float* s = scr + (size_t)(r - TP) * DM + i * 256 + lane * 4;
;                         for (int q = 0; q < nsl; ++q) v[b][i] = v[b][i] + *(const f32x4*)(s + (size_t)q * TS * DM);
;                         if (!final_inplace) *(f32x4*)(X + (size_t)r * DM + i * 256 + lane * 4) = v[b][i]; }
.LBB0_706:
	s_or_b64 exec, exec, s[4:5]
	v_add_u32_e32 v16, 0xffffc000, v102
	v_lshlrev_b64 v[100:101], 12, v[16:17]
	v_cmp_lt_i32_e64 s[46:47], s15, v102
	v_lshl_add_u64 v[100:101], v[82:83], 0, v[100:101]
	s_and_saveexec_b64 s[4:5], s[46:47]
	s_cbranch_execz .LBB0_711
	global_load_dwordx4 v[120:123], v[100:101], off
	global_load_dwordx4 v[124:127], v[100:101], off offset:1024
	global_load_dwordx4 v[128:131], v[100:101], off offset:2048
	global_load_dwordx4 v[132:135], v[100:101], off offset:3072
	v_add_co_u32_e32 v136, vcc, 0x200000, v100
	s_nop 1
	v_addc_co_u32_e32 v137, vcc, 0, v101, vcc
	global_load_dwordx4 v[140:143], v[136:137], off
	global_load_dwordx4 v[144:147], v[136:137], off offset:1024
	global_load_dwordx4 v[148:151], v[136:137], off offset:2048
	global_load_dwordx4 v[152:155], v[136:137], off offset:3072
	v_add_co_u32_e32 v188, vcc, 0x400000, v100
	s_nop 1
	v_addc_co_u32_e32 v189, vcc, 0, v101, vcc
	global_load_dwordx4 v[156:159], v[188:189], off
	global_load_dwordx4 v[160:163], v[188:189], off offset:1024
	global_load_dwordx4 v[164:167], v[188:189], off offset:2048
	global_load_dwordx4 v[168:171], v[188:189], off offset:3072
	v_add_co_u32_e32 v190, vcc, 0x600000, v100
	s_nop 1
	v_addc_co_u32_e32 v191, vcc, 0, v101, vcc
	global_load_dwordx4 v[172:175], v[190:191], off
	global_load_dwordx4 v[176:179], v[190:191], off offset:1024
	global_load_dwordx4 v[180:183], v[190:191], off offset:2048
	global_load_dwordx4 v[184:187], v[190:191], off offset:3072
	s_waitcnt vmcnt(0)
	v_pk_add_f32 v[78:79], v[78:79], v[120:121]
	v_pk_add_f32 v[80:81], v[80:81], v[122:123]
	v_pk_add_f32 v[78:79], v[78:79], v[140:141]
	v_pk_add_f32 v[80:81], v[80:81], v[142:143]
	v_pk_add_f32 v[78:79], v[78:79], v[156:157]
	v_pk_add_f32 v[80:81], v[80:81], v[158:159]
	v_pk_add_f32 v[78:79], v[78:79], v[172:173]
	v_pk_add_f32 v[80:81], v[80:81], v[174:175]
	v_pk_add_f32 v[74:75], v[74:75], v[124:125]
	v_pk_add_f32 v[76:77], v[76:77], v[126:127]
	v_pk_add_f32 v[74:75], v[74:75], v[144:145]
	v_pk_add_f32 v[76:77], v[76:77], v[146:147]
	v_pk_add_f32 v[74:75], v[74:75], v[160:161]
	v_pk_add_f32 v[76:77], v[76:77], v[162:163]
	v_pk_add_f32 v[74:75], v[74:75], v[176:177]
	v_pk_add_f32 v[76:77], v[76:77], v[178:179]
	v_pk_add_f32 v[70:71], v[70:71], v[128:129]
	v_pk_add_f32 v[72:73], v[72:73], v[130:131]
	v_pk_add_f32 v[70:71], v[70:71], v[148:149]
	v_pk_add_f32 v[72:73], v[72:73], v[150:151]
	v_pk_add_f32 v[70:71], v[70:71], v[164:165]
	v_pk_add_f32 v[72:73], v[72:73], v[166:167]
	v_pk_add_f32 v[70:71], v[70:71], v[180:181]
	v_pk_add_f32 v[72:73], v[72:73], v[182:183]
	v_pk_add_f32 v[66:67], v[66:67], v[132:133]
	v_pk_add_f32 v[68:69], v[68:69], v[134:135]
	v_pk_add_f32 v[66:67], v[66:67], v[152:153]
	v_pk_add_f32 v[68:69], v[68:69], v[154:155]
	v_pk_add_f32 v[66:67], v[66:67], v[168:169]
	v_pk_add_f32 v[68:69], v[68:69], v[170:171]
	v_pk_add_f32 v[66:67], v[66:67], v[184:185]
	v_pk_add_f32 v[68:69], v[68:69], v[186:187]
	v_add_co_u32_e32 v192, vcc, 0x800000, v100
	s_nop 1
	v_addc_co_u32_e32 v193, vcc, 0, v101, vcc
	global_load_dwordx4 v[120:123], v[192:193], off
	global_load_dwordx4 v[124:127], v[192:193], off offset:1024
	global_load_dwordx4 v[128:131], v[192:193], off offset:2048
	global_load_dwordx4 v[132:135], v[192:193], off offset:3072
	v_add_co_u32_e32 v136, vcc, 0xa00000, v100
	s_nop 1
	v_addc_co_u32_e32 v137, vcc, 0, v101, vcc
	global_load_dwordx4 v[140:143], v[136:137], off
	global_load_dwordx4 v[144:147], v[136:137], off offset:1024
	global_load_dwordx4 v[148:151], v[136:137], off offset:2048
	global_load_dwordx4 v[152:155], v[136:137], off offset:3072
	v_add_co_u32_e32 v188, vcc, 0xc00000, v100
	s_nop 1
	v_addc_co_u32_e32 v189, vcc, 0, v101, vcc
	global_load_dwordx4 v[156:159], v[188:189], off
	global_load_dwordx4 v[160:163], v[188:189], off offset:1024
	global_load_dwordx4 v[164:167], v[188:189], off offset:2048
	global_load_dwordx4 v[168:171], v[188:189], off offset:3072
	v_add_co_u32_e32 v190, vcc, 0xe00000, v100
	s_nop 1
	v_addc_co_u32_e32 v191, vcc, 0, v101, vcc
	global_load_dwordx4 v[172:175], v[190:191], off
	global_load_dwordx4 v[176:179], v[190:191], off offset:1024
	global_load_dwordx4 v[180:183], v[190:191], off offset:2048
	global_load_dwordx4 v[184:187], v[190:191], off offset:3072
	s_waitcnt vmcnt(0)
	v_pk_add_f32 v[78:79], v[78:79], v[120:121]
	v_pk_add_f32 v[80:81], v[80:81], v[122:123]
	v_pk_add_f32 v[78:79], v[78:79], v[140:141]
	v_pk_add_f32 v[80:81], v[80:81], v[142:143]
	v_pk_add_f32 v[78:79], v[78:79], v[156:157]
	v_pk_add_f32 v[80:81], v[80:81], v[158:159]
	v_pk_add_f32 v[78:79], v[78:79], v[172:173]
	v_pk_add_f32 v[80:81], v[80:81], v[174:175]
	v_pk_add_f32 v[74:75], v[74:75], v[124:125]
	v_pk_add_f32 v[76:77], v[76:77], v[126:127]
	v_pk_add_f32 v[74:75], v[74:75], v[144:145]
	v_pk_add_f32 v[76:77], v[76:77], v[146:147]
	v_pk_add_f32 v[74:75], v[74:75], v[160:161]
	v_pk_add_f32 v[76:77], v[76:77], v[162:163]
	v_pk_add_f32 v[74:75], v[74:75], v[176:177]
	v_pk_add_f32 v[76:77], v[76:77], v[178:179]
	v_pk_add_f32 v[70:71], v[70:71], v[128:129]
	v_pk_add_f32 v[72:73], v[72:73], v[130:131]
	v_pk_add_f32 v[70:71], v[70:71], v[148:149]
	v_pk_add_f32 v[72:73], v[72:73], v[150:151]
	v_pk_add_f32 v[70:71], v[70:71], v[164:165]
	v_pk_add_f32 v[72:73], v[72:73], v[166:167]
	v_pk_add_f32 v[70:71], v[70:71], v[180:181]
	v_pk_add_f32 v[72:73], v[72:73], v[182:183]
	v_pk_add_f32 v[66:67], v[66:67], v[132:133]
	v_pk_add_f32 v[68:69], v[68:69], v[134:135]
	v_pk_add_f32 v[66:67], v[66:67], v[152:153]
	v_pk_add_f32 v[68:69], v[68:69], v[154:155]
	v_pk_add_f32 v[66:67], v[66:67], v[168:169]
	v_pk_add_f32 v[68:69], v[68:69], v[170:171]
	v_pk_add_f32 v[66:67], v[66:67], v[184:185]
	v_pk_add_f32 v[68:69], v[68:69], v[186:187]

;     ...
;         for (int b = 0; b < 4; ++b) { const int r = r0 + b * nw;
;             if (r < TT) {
;                 float ss = 0.f;
; #pragma unroll
;                 for (int i = 0; i < 4; ++i) {
;                     if (nsl && r >= TP) {
;                         const float* s = scr + (size_t)(r - TP) * DM + i * 256 + lane * 4;
;                         for (int q = 0; q < nsl; ++q) v[b][i] = v[b][i] + *(const f32x4*)(s + (size_t)q * TS * DM);
;                         if (!final_inplace) *(f32x4*)(X + (size_t)r * DM + i * 256 + lane * 4) = v[b][i]; }
.LBB0_713:
	s_or_b64 exec, exec, s[4:5]
	s_and_saveexec_b64 s[4:5], s[40:41]
	s_cbranch_execz .LBB0_699
	s_branch .LBB0_729
.LBB0_717:
	v_add_u32_e32 v16, 0xffffc000, v105
	v_lshlrev_b64 v[66:67], 12, v[16:17]
	v_cmp_lt_i32_e64 s[44:45], s15, v105
	v_lshl_add_u64 v[66:67], v[82:83], 0, v[66:67]
	s_and_saveexec_b64 s[6:7], s[44:45]
	s_cbranch_execnz .LBB0_733
	s_or_b64 exec, exec, s[6:7]
	s_and_saveexec_b64 s[6:7], s[44:45]
	s_cbranch_execnz .LBB0_734

;     ...
;             if (r < TT) { const float* src = srcP ? (r < TP ? srcP + (size_t)r * DM : srcS + (size_t)(r - TP) * DM) : X + (size_t)r * DM;
; #pragma unroll
;                 for (int i = 0; i < 4; ++i) v[b][i] = *(const f32x4*)(src + i * 256 + lane * 4); } }
; #pragma unroll
;         for (int b = 0; b < 4; ++b) { const int r = r0 + b * nw;
;             if (r < TT) {
;                 float ss = 0.f;
; #pragma unroll
;                 for (int i = 0; i < 4; ++i) {
;                     if (nsl && r >= TP) {
;                         const float* s = scr + (size_t)(r - TP) * DM + i * 256 + lane * 4;
;                         for (int q = 0; q < nsl; ++q) v[b][i] = v[b][i] + *(const f32x4*)(s + (size_t)q * TS * DM);
;                         if (!final_inplace) *(f32x4*)(X + (size_t)r * DM + i * 256 + lane * 4) = v[b][i]; }
.LBB0_755:
	s_or_b64 exec, exec, s[4:5]
	v_add_u32_e32 v16, 0xffffc000, v82
	v_lshlrev_b64 v[108:109], 12, v[16:17]
	v_mov_b32_e32 v83, v17
	v_lshl_add_u64 v[110:111], v[84:85], 0, v[108:109]
	v_lshlrev_b64 v[108:109], 12, v[82:83]
	v_cmp_lt_i32_e64 s[46:47], s15, v82
	v_lshl_add_u64 v[108:109], v[86:87], 0, v[108:109]
	s_and_saveexec_b64 s[4:5], s[46:47]
	s_cbranch_execz .LBB0_760
	global_load_dwordx4 v[120:123], v[110:111], off
	global_load_dwordx4 v[124:127], v[110:111], off offset:1024
	global_load_dwordx4 v[128:131], v[110:111], off offset:2048
	global_load_dwordx4 v[132:135], v[110:111], off offset:3072
	v_add_co_u32_e32 v136, vcc, 0x200000, v110
	s_nop 1
	v_addc_co_u32_e32 v137, vcc, 0, v111, vcc
	global_load_dwordx4 v[140:143], v[136:137], off
	global_load_dwordx4 v[144:147], v[136:137], off offset:1024
	global_load_dwordx4 v[148:151], v[136:137], off offset:2048
	global_load_dwordx4 v[152:155], v[136:137], off offset:3072
	v_add_co_u32_e32 v188, vcc, 0x400000, v110
	s_nop 1
	v_addc_co_u32_e32 v189, vcc, 0, v111, vcc
	global_load_dwordx4 v[156:159], v[188:189], off
	global_load_dwordx4 v[160:163], v[188:189], off offset:1024
	global_load_dwordx4 v[164:167], v[188:189], off offset:2048
	global_load_dwordx4 v[168:171], v[188:189], off offset:3072
	v_add_co_u32_e32 v190, vcc, 0x600000, v110
	s_nop 1
	v_addc_co_u32_e32 v191, vcc, 0, v111, vcc
	global_load_dwordx4 v[172:175], v[190:191], off
	global_load_dwordx4 v[176:179], v[190:191], off offset:1024
	global_load_dwordx4 v[180:183], v[190:191], off offset:2048
	global_load_dwordx4 v[184:187], v[190:191], off offset:3072
	s_waitcnt vmcnt(0)
	v_pk_add_f32 v[78:79], v[78:79], v[120:121]
	v_pk_add_f32 v[80:81], v[80:81], v[122:123]
	v_pk_add_f32 v[78:79], v[78:79], v[140:141]
	v_pk_add_f32 v[80:81], v[80:81], v[142:143]
	v_pk_add_f32 v[78:79], v[78:79], v[156:157]
	v_pk_add_f32 v[80:81], v[80:81], v[158:159]
	v_pk_add_f32 v[78:79], v[78:79], v[172:173]
	v_pk_add_f32 v[80:81], v[80:81], v[174:175]
	v_pk_add_f32 v[74:75], v[74:75], v[124:125]
	v_pk_add_f32 v[76:77], v[76:77], v[126:127]
	v_pk_add_f32 v[74:75], v[74:75], v[144:145]
	v_pk_add_f32 v[76:77], v[76:77], v[146:147]
	v_pk_add_f32 v[74:75], v[74:75], v[160:161]
	v_pk_add_f32 v[76:77], v[76:77], v[162:163]
	v_pk_add_f32 v[74:75], v[74:75], v[176:177]
	v_pk_add_f32 v[76:77], v[76:77], v[178:179]
	v_pk_add_f32 v[70:71], v[70:71], v[128:129]
	v_pk_add_f32 v[72:73], v[72:73], v[130:131]
	v_pk_add_f32 v[70:71], v[70:71], v[148:149]
	v_pk_add_f32 v[72:73], v[72:73], v[150:151]
	v_pk_add_f32 v[70:71], v[70:71], v[164:165]
	v_pk_add_f32 v[72:73], v[72:73], v[166:167]
	v_pk_add_f32 v[70:71], v[70:71], v[180:181]
	v_pk_add_f32 v[72:73], v[72:73], v[182:183]
	v_pk_add_f32 v[66:67], v[66:67], v[132:133]
	v_pk_add_f32 v[68:69], v[68:69], v[134:135]
	v_pk_add_f32 v[66:67], v[66:67], v[152:153]
	v_pk_add_f32 v[68:69], v[68:69], v[154:155]
	v_pk_add_f32 v[66:67], v[66:67], v[168:169]
	v_pk_add_f32 v[68:69], v[68:69], v[170:171]
	v_pk_add_f32 v[66:67], v[66:67], v[184:185]
	v_pk_add_f32 v[68:69], v[68:69], v[186:187]
	v_add_co_u32_e32 v192, vcc, 0x800000, v110
	s_nop 1
	v_addc_co_u32_e32 v193, vcc, 0, v111, vcc
	global_load_dwordx4 v[120:123], v[192:193], off
	global_load_dwordx4 v[124:127], v[192:193], off offset:1024
	global_load_dwordx4 v[128:131], v[192:193], off offset:2048
	global_load_dwordx4 v[132:135], v[192:193], off offset:3072
	v_add_co_u32_e32 v136, vcc, 0xa00000, v110
	s_nop 1
	v_addc_co_u32_e32 v137, vcc, 0, v111, vcc
	global_load_dwordx4 v[140:143], v[136:137], off
	global_load_dwordx4 v[144:147], v[136:137], off offset:1024
	global_load_dwordx4 v[148:151], v[136:137], off offset:2048
	global_load_dwordx4 v[152:155], v[136:137], off offset:3072
	v_add_co_u32_e32 v188, vcc, 0xc00000, v110
	s_nop 1
	v_addc_co_u32_e32 v189, vcc, 0, v111, vcc
	global_load_dwordx4 v[156:159], v[188:189], off
	global_load_dwordx4 v[160:163], v[188:189], off offset:1024
	global_load_dwordx4 v[164:167], v[188:189], off offset:2048
	global_load_dwordx4 v[168:171], v[188:189], off offset:3072
	v_add_co_u32_e32 v190, vcc, 0xe00000, v110
	s_nop 1
	v_addc_co_u32_e32 v191, vcc, 0, v111, vcc
	global_load_dwordx4 v[172:175], v[190:191], off
	global_load_dwordx4 v[176:179], v[190:191], off offset:1024
	global_load_dwordx4 v[180:183], v[190:191], off offset:2048
	global_load_dwordx4 v[184:187], v[190:191], off offset:3072
	s_waitcnt vmcnt(0)
	v_pk_add_f32 v[78:79], v[78:79], v[120:121]
	v_pk_add_f32 v[80:81], v[80:81], v[122:123]
	v_pk_add_f32 v[78:79], v[78:79], v[140:141]
	v_pk_add_f32 v[80:81], v[80:81], v[142:143]
	v_pk_add_f32 v[78:79], v[78:79], v[156:157]
	v_pk_add_f32 v[80:81], v[80:81], v[158:159]
	v_pk_add_f32 v[78:79], v[78:79], v[172:173]
	v_pk_add_f32 v[80:81], v[80:81], v[174:175]
	v_pk_add_f32 v[74:75], v[74:75], v[124:125]
	v_pk_add_f32 v[76:77], v[76:77], v[126:127]
	v_pk_add_f32 v[74:75], v[74:75], v[144:145]
	v_pk_add_f32 v[76:77], v[76:77], v[146:147]
	v_pk_add_f32 v[74:75], v[74:75], v[160:161]
	v_pk_add_f32 v[76:77], v[76:77], v[162:163]
	v_pk_add_f32 v[74:75], v[74:75], v[176:177]
	v_pk_add_f32 v[76:77], v[76:77], v[178:179]
	v_pk_add_f32 v[70:71], v[70:71], v[128:129]
	v_pk_add_f32 v[72:73], v[72:73], v[130:131]
	v_pk_add_f32 v[70:71], v[70:71], v[148:149]
	v_pk_add_f32 v[72:73], v[72:73], v[150:151]
	v_pk_add_f32 v[70:71], v[70:71], v[164:165]
	v_pk_add_f32 v[72:73], v[72:73], v[166:167]
	v_pk_add_f32 v[70:71], v[70:71], v[180:181]
	v_pk_add_f32 v[72:73], v[72:73], v[182:183]
	v_pk_add_f32 v[66:67], v[66:67], v[132:133]
	v_pk_add_f32 v[68:69], v[68:69], v[134:135]
	v_pk_add_f32 v[66:67], v[66:67], v[152:153]
	v_pk_add_f32 v[68:69], v[68:69], v[154:155]
	v_pk_add_f32 v[66:67], v[66:67], v[168:169]
	v_pk_add_f32 v[68:69], v[68:69], v[170:171]
	v_pk_add_f32 v[66:67], v[66:67], v[184:185]
	v_pk_add_f32 v[68:69], v[68:69], v[186:187]
	global_store_dwordx4 v[108:109], v[78:81], off
	global_store_dwordx4 v[108:109], v[74:77], off offset:1024
	global_store_dwordx4 v[108:109], v[70:73], off offset:2048
	global_store_dwordx4 v[108:109], v[66:69], off offset:3072

;     ...
;         for (int b = 0; b < 4; ++b) { const int r = r0 + b * nw;
;             if (r < TT) {
;                 float ss = 0.f;
; #pragma unroll
;                 for (int i = 0; i < 4; ++i) {
;                     if (nsl && r >= TP) {
;                         const float* s = scr + (size_t)(r - TP) * DM + i * 256 + lane * 4;
;                         for (int q = 0; q < nsl; ++q) v[b][i] = v[b][i] + *(const f32x4*)(s + (size_t)q * TS * DM);
;                         if (!final_inplace) *(f32x4*)(X + (size_t)r * DM + i * 256 + lane * 4) = v[b][i]; }
.LBB0_762:
	s_or_b64 exec, exec, s[4:5]
	s_and_saveexec_b64 s[4:5], s[40:41]
	s_cbranch_execz .LBB0_748
	s_branch .LBB0_778
.LBB0_766:
	v_add_u32_e32 v16, 0xffffc000, v106
	v_lshlrev_b64 v[66:67], 12, v[16:17]
	v_mov_b32_e32 v107, v17
	v_lshl_add_u64 v[68:69], v[84:85], 0, v[66:67]
	v_lshlrev_b64 v[66:67], 12, v[106:107]
	v_cmp_lt_i32_e64 s[44:45], s15, v106
	v_lshl_add_u64 v[66:67], v[86:87], 0, v[66:67]
	s_and_saveexec_b64 s[6:7], s[44:45]
	s_cbranch_execnz .LBB0_782
	s_or_b64 exec, exec, s[6:7]
	s_and_saveexec_b64 s[6:7], s[44:45]
	s_cbranch_execnz .LBB0_783

;     __device__ __forceinline__ void operator()(const f32x4 (&acc)[2][2][4][2], const Unit& u, int wr, int wc, int fr, int fq) const {
;         if (mode == 2) {
;             float* C = (float*)out;
;             const int row0 = u.pm * BM + wr * 64 + fr, col0 = u.pn * BM + wc * 32 + 4 * fq;
; #pragma unroll
;             for (int ai = 0; ai < 2; ++ai)
; #pragma unroll
;                 for (int m = 0; m < 4; ++m) { float* rowp = C + (size_t)(row0 + ai * HALF + m * 16) * ldc + col0;
; #pragma unroll
;                     for (int bj = 0; bj < 2; ++bj)
; #pragma unroll
;                         for (int n = 0; n < 2; ++n) { float* q = rowp + bj * HALF + n * 16; const f32x4 v = acc[ai][bj][m][n];
;                             if (u.k0 < 0) *(f32x4*)(scr + (size_t)u.sl * TS * DM + (q - C) - (size_t)64 * BM * ldc) = v;
;                             else *(f32x4*)q = *(f32x4*)q + v; } }
.LBB0_864:
	s_and_b64 vcc, exec, s[6:7]
	s_cbranch_vccz .LBB0_814
	v_or_b32_e32 v16, s3, v160
	v_lshl_add_u64 v[146:147], v[16:17], 2, s[52:53]
	v_lshl_add_u64 v[148:149], v[144:145], 2, v[146:147]
	s_mov_b64 s[6:7], -1
	s_and_b64 vcc, exec, s[4:5]
	s_cbranch_vccz .LBB0_867
	s_mov_b64 s[6:7], 0x10000
	s_mov_b64 s[40:41], 0x80000
	v_lshl_add_u64 v[150:151], v[148:149], 0, s[6:7]
	v_lshl_add_u64 v[162:163], v[148:149], 0, s[40:41]
	v_lshl_add_u64 v[152:153], v[150:151], 0, s[6:7]
	v_lshl_add_u64 v[164:165], v[162:163], 0, s[6:7]
	v_lshl_add_u64 v[154:155], v[152:153], 0, s[6:7]
	v_lshl_add_u64 v[198:199], v[164:165], 0, s[6:7]
	global_load_dwordx4 v[166:169], v[148:149], off
	global_load_dwordx4 v[170:173], v[148:149], off offset:64
	global_load_dwordx4 v[174:177], v[148:149], off offset:512
	global_load_dwordx4 v[178:181], v[148:149], off offset:576
	v_lshl_add_u64 v[200:201], v[198:199], 0, s[6:7]
	global_load_dwordx4 v[182:185], v[150:151], off
	global_load_dwordx4 v[186:189], v[150:151], off offset:64
	global_load_dwordx4 v[190:193], v[150:151], off offset:512
	global_load_dwordx4 v[194:197], v[150:151], off offset:576
	s_waitcnt vmcnt(4)
	v_pk_add_f32 v[126:127], v[126:127], v[166:167]
	v_pk_add_f32 v[128:129], v[128:129], v[168:169]
	v_pk_add_f32 v[122:123], v[122:123], v[170:171]
	v_pk_add_f32 v[124:125], v[124:125], v[172:173]
	v_pk_add_f32 v[118:119], v[118:119], v[174:175]
	v_pk_add_f32 v[120:121], v[120:121], v[176:177]
	v_pk_add_f32 v[114:115], v[114:115], v[178:179]
	v_pk_add_f32 v[116:117], v[116:117], v[180:181]
	global_store_dwordx4 v[148:149], v[126:129], off
	global_store_dwordx4 v[148:149], v[122:125], off offset:64
	global_store_dwordx4 v[148:149], v[118:121], off offset:512
	global_store_dwordx4 v[148:149], v[114:117], off offset:576
	global_load_dwordx4 v[166:169], v[152:153], off
	global_load_dwordx4 v[170:173], v[152:153], off offset:64
	global_load_dwordx4 v[174:177], v[152:153], off offset:512
	global_load_dwordx4 v[178:181], v[152:153], off offset:576
	s_waitcnt vmcnt(8)
	v_pk_add_f32 v[110:111], v[110:111], v[182:183]
	v_pk_add_f32 v[112:113], v[112:113], v[184:185]
	v_pk_add_f32 v[106:107], v[106:107], v[186:187]
	v_pk_add_f32 v[108:109], v[108:109], v[188:189]
	v_pk_add_f32 v[102:103], v[102:103], v[190:191]
	v_pk_add_f32 v[104:105], v[104:105], v[192:193]
	v_pk_add_f32 v[98:99], v[98:99], v[194:195]
	v_pk_add_f32 v[100:101], v[100:101], v[196:197]
	global_store_dwordx4 v[150:151], v[110:113], off
	global_store_dwordx4 v[150:151], v[106:109], off offset:64
	global_store_dwordx4 v[150:151], v[102:105], off offset:512
	global_store_dwordx4 v[150:151], v[98:101], off offset:576
	global_load_dwordx4 v[182:185], v[154:155], off
	global_load_dwordx4 v[186:189], v[154:155], off offset:64
	global_load_dwordx4 v[190:193], v[154:155], off offset:512
	global_load_dwordx4 v[194:197], v[154:155], off offset:576
	s_waitcnt vmcnt(8)
	v_pk_add_f32 v[94:95], v[94:95], v[166:167]
	v_pk_add_f32 v[96:97], v[96:97], v[168:169]
	v_pk_add_f32 v[90:91], v[90:91], v[170:171]
	v_pk_add_f32 v[92:93], v[92:93], v[172:173]
	v_pk_add_f32 v[86:87], v[86:87], v[174:175]
	v_pk_add_f32 v[88:89], v[88:89], v[176:177]
	v_pk_add_f32 v[82:83], v[82:83], v[178:179]
	v_pk_add_f32 v[84:85], v[84:85], v[180:181]
	global_store_dwordx4 v[152:153], v[94:97], off
	global_store_dwordx4 v[152:153], v[90:93], off offset:64
	global_store_dwordx4 v[152:153], v[86:89], off offset:512
	global_store_dwordx4 v[152:153], v[82:85], off offset:576
	global_load_dwordx4 v[166:169], v[162:163], off
	global_load_dwordx4 v[170:173], v[162:163], off offset:64
	global_load_dwordx4 v[174:177], v[162:163], off offset:512
	global_load_dwordx4 v[178:181], v[162:163], off offset:576
	s_waitcnt vmcnt(8)
;     __device__ __forceinline__ void operator()(const f32x4 (&acc)[2][2][4][2], const Unit& u, int wr, int wc, int fr, int fq) const {
;         if (mode == 2) {
;             float* C = (float*)out;
;             const int row0 = u.pm * BM + wr * 64 + fr, col0 = u.pn * BM + wc * 32 + 4 * fq;
; #pragma unroll
;             for (int ai = 0; ai < 2; ++ai)
; #pragma unroll
;                 for (int m = 0; m < 4; ++m) { float* rowp = C + (size_t)(row0 + ai * HALF + m * 16) * ldc + col0;
; #pragma unroll
;                     for (int bj = 0; bj < 2; ++bj)
; #pragma unroll
;                         for (int n = 0; n < 2; ++n) { float* q = rowp + bj * HALF + n * 16; const f32x4 v = acc[ai][bj][m][n];
;                             if (u.k0 < 0) *(f32x4*)(scr + (size_t)u.sl * TS * DM + (q - C) - (size_t)64 * BM * ldc) = v;
;                             else *(f32x4*)q = *(f32x4*)q + v; } }
	v_pk_add_f32 v[78:79], v[78:79], v[182:183]
	v_pk_add_f32 v[80:81], v[80:81], v[184:185]
	v_pk_add_f32 v[74:75], v[74:75], v[186:187]
	v_pk_add_f32 v[76:77], v[76:77], v[188:189]
	v_pk_add_f32 v[70:71], v[70:71], v[190:191]
	v_pk_add_f32 v[72:73], v[72:73], v[192:193]
	v_pk_add_f32 v[66:67], v[66:67], v[194:195]
	v_pk_add_f32 v[68:69], v[68:69], v[196:197]
	global_store_dwordx4 v[154:155], v[78:81], off
	global_store_dwordx4 v[154:155], v[74:77], off offset:64
	global_store_dwordx4 v[154:155], v[70:73], off offset:512
	global_store_dwordx4 v[154:155], v[66:69], off offset:576
	global_load_dwordx4 v[182:185], v[164:165], off
	global_load_dwordx4 v[186:189], v[164:165], off offset:64
	global_load_dwordx4 v[190:193], v[164:165], off offset:512
	global_load_dwordx4 v[194:197], v[164:165], off offset:576
	s_waitcnt vmcnt(8)
	v_pk_add_f32 v[62:63], v[62:63], v[166:167]
	v_pk_add_f32 v[64:65], v[64:65], v[168:169]
	v_pk_add_f32 v[58:59], v[58:59], v[170:171]
	v_pk_add_f32 v[60:61], v[60:61], v[172:173]
	v_pk_add_f32 v[54:55], v[54:55], v[174:175]
	v_pk_add_f32 v[56:57], v[56:57], v[176:177]
	v_pk_add_f32 v[50:51], v[50:51], v[178:179]
	v_pk_add_f32 v[52:53], v[52:53], v[180:181]
	global_store_dwordx4 v[162:163], v[62:65], off
	global_store_dwordx4 v[162:163], v[58:61], off offset:64
	global_store_dwordx4 v[162:163], v[54:57], off offset:512
	global_store_dwordx4 v[162:163], v[50:53], off offset:576
	global_load_dwordx4 v[166:169], v[198:199], off
	global_load_dwordx4 v[170:173], v[198:199], off offset:64
	global_load_dwordx4 v[174:177], v[198:199], off offset:512
	global_load_dwordx4 v[178:181], v[198:199], off offset:576
	s_waitcnt vmcnt(8)
	v_pk_add_f32 v[46:47], v[46:47], v[182:183]
	v_pk_add_f32 v[48:49], v[48:49], v[184:185]
	v_pk_add_f32 v[42:43], v[42:43], v[186:187]
	v_pk_add_f32 v[44:45], v[44:45], v[188:189]
	v_pk_add_f32 v[38:39], v[38:39], v[190:191]
	v_pk_add_f32 v[40:41], v[40:41], v[192:193]
	v_pk_add_f32 v[34:35], v[34:35], v[194:195]
	v_pk_add_f32 v[36:37], v[36:37], v[196:197]
	global_store_dwordx4 v[164:165], v[46:49], off
	global_store_dwordx4 v[164:165], v[42:45], off offset:64
	global_store_dwordx4 v[164:165], v[38:41], off offset:512
	global_store_dwordx4 v[164:165], v[34:37], off offset:576
	global_load_dwordx4 v[182:185], v[200:201], off
	global_load_dwordx4 v[186:189], v[200:201], off offset:64
	global_load_dwordx4 v[190:193], v[200:201], off offset:512
	global_load_dwordx4 v[194:197], v[200:201], off offset:576
	s_waitcnt vmcnt(8)
	v_pk_add_f32 v[30:31], v[30:31], v[166:167]
	v_pk_add_f32 v[32:33], v[32:33], v[168:169]
	v_pk_add_f32 v[26:27], v[26:27], v[170:171]
	v_pk_add_f32 v[28:29], v[28:29], v[172:173]
	v_pk_add_f32 v[22:23], v[22:23], v[174:175]
	v_pk_add_f32 v[24:25], v[24:25], v[176:177]
	v_pk_add_f32 v[18:19], v[18:19], v[178:179]
	v_pk_add_f32 v[20:21], v[20:21], v[180:181]
	global_store_dwordx4 v[198:199], v[30:33], off
	global_store_dwordx4 v[198:199], v[26:29], off offset:64
	global_store_dwordx4 v[198:199], v[22:25], off offset:512
	global_store_dwordx4 v[198:199], v[18:21], off offset:576
	s_waitcnt vmcnt(4)
	v_pk_add_f32 v[12:13], v[12:13], v[182:183]
	v_pk_add_f32 v[14:15], v[14:15], v[184:185]
	v_pk_add_f32 v[8:9], v[8:9], v[186:187]
	v_pk_add_f32 v[10:11], v[10:11], v[188:189]
	v_pk_add_f32 v[4:5], v[4:5], v[190:191]
	v_pk_add_f32 v[6:7], v[6:7], v[192:193]
	v_pk_add_f32 v[0:1], v[0:1], v[194:195]
	v_pk_add_f32 v[2:3], v[2:3], v[196:197]
	global_store_dwordx4 v[200:201], v[12:15], off
	global_store_dwordx4 v[200:201], v[8:11], off offset:64
	global_store_dwordx4 v[200:201], v[4:7], off offset:512
	global_store_dwordx4 v[200:201], v[0:3], off offset:576
	s_branch .LBB0_814
	global_load_dwordx4 v[150:153], v[148:149], off
	s_mov_b64 s[6:7], 0
	s_waitcnt vmcnt(0)
	v_pk_add_f32 v[152:153], v[128:129], v[152:153]
	v_pk_add_f32 v[150:151], v[126:127], v[150:151]
	global_store_dwordx4 v[148:149], v[150:153], off
